# v133 + first-sync follower invalidate at arrival + GEMM2-phase param loads issued together + retention norm reductions via DPP
# speedup vs baseline: 1.0273x; 1.0008x over previous
.Lgb_ready:
	v_min_u32_e32 v2, 1, v2
	v_min_u32_e32 v3, 1, v3
	v_min_u32_e32 v4, 1, v4
	v_min_u32_e32 v5, 1, v5
	v_min_u32_e32 v6, 1, v6
	v_min_u32_e32 v7, 1, v7
	v_min_u32_e32 v8, 1, v8
	v_min_u32_e32 v9, 1, v9
	v_min_u32_e32 v10, 1, v10
	v_min_u32_e32 v11, 1, v11
	v_min_u32_e32 v12, 1, v12
	v_min_u32_e32 v13, 1, v13
	v_min_u32_e32 v14, 1, v14
	v_min_u32_e32 v15, 1, v15
	v_min_u32_e32 v16, 1, v16
	v_min_u32_e32 v17, 1, v17
	v_add3_u32 v0, v2, v3, v4
	v_add3_u32 v0, v0, v5, v6
	v_add3_u32 v0, v0, v7, v8
	v_add3_u32 v0, v0, v9, v10
	v_add3_u32 v0, v0, v11, v12
	v_add3_u32 v0, v0, v13, v14
	v_add3_u32 v0, v0, v15, v16
	v_add_u32_e32 v0, v0, v17
	v_max_u32_e32 v0, 1, v0
	v_max_u32_e32 v18, 1, v18
	v_mov_b32_e32 v2, 0x24010
	ds_write_b32 v2, v18
	ds_write_b32 v2, v0 offset:4
	s_add_u32 s10, s6, 0x1000
	s_addc_u32 s11, s7, 0
	s_add_u32 s8, s6, 0x2000
	s_addc_u32 s9, s7, 0
	s_add_u32 s12, s56, 0x3000
	s_addc_u32 s13, s57, 0
	v_mov_b32_e32 v2, 1
	global_atomic_add v3, v1, v2, s[10:11] offset:1024 sc0
	buffer_inv sc1
	s_waitcnt vmcnt(0)
	v_add_u32_e32 v3, 1, v3
	v_cmp_ne_u32_e32 vcc, v3, v18
	s_cbranch_vccnz .Lgb_follow
	buffer_wbl2 sc1
	s_waitcnt vmcnt(0) lgkmcnt(0)
	global_atomic_add v3, v1, v2, s[12:13] offset:1024 sc0
	s_waitcnt vmcnt(0)
	v_add_u32_e32 v3, 1, v3
	v_cmp_ne_u32_e32 vcc, v3, v0
	s_cbranch_vccnz .Lgb_topwait
	global_atomic_add v1, v2, s[12:13] offset:1280
	s_branch .Lgb_topdone

.Lgb_fspin:
	s_sleep 1
	global_load_dword v3, v1, s[8:9] offset:1024 sc1
	s_add_i32 s1, s1, 1
	s_waitcnt vmcnt(0)
	v_cmp_ne_u32_e32 vcc, 0, v3
	s_cbranch_vccnz .Lgb_fdone
	s_cmp_lt_u32 s1, 0x4000
	s_cbranch_scc1 .Lgb_fspin
.Lgb_fdone:
	s_waitcnt vmcnt(0)
.LBB0_101:
	s_or_b64 exec, exec, s[4:5]
	s_cmpk_lt_i32 s2, 0x400
	s_cselect_b64 s[18:19], -1, 0
	s_cmpk_lt_i32 s2, 0x3a0
	s_cselect_b64 s[4:5], -1, 0
	s_add_i32 s1, s2, 0x60
	s_and_b32 s3, s1, 0xff
	s_mulk_i32 s3, 0xab
	v_writelane_b32 v253, s4, 1
	s_bfe_u32 s3, s3, 0x4000c
	s_mul_i32 s51, s51, s50
	v_writelane_b32 v253, s5, 2
	s_mul_i32 s4, s3, 24
	s_sub_i32 s1, s1, s4
	s_add_i32 s3, s3, 29
	s_and_b32 s1, s1, 0xff
	s_and_b32 s3, s3, 63
	v_writelane_b32 v253, s3, 3
	s_add_i32 s3, s1, 4
	s_cmp_lt_u32 s1, 12
	s_cselect_b32 s1, s1, s3
	v_writelane_b32 v253, s1, 4
	s_ashr_i32 s1, s2, 31
	s_lshr_b32 s1, s1, 29
	s_add_i32 s1, s2, s1
	s_ashr_i32 s5, s1, 3
	s_and_b32 s1, s1, -8
	s_sub_i32 s1, s2, s1
	s_lshl_b32 s3, s1, 5
	s_cmp_lt_i32 s1, 0
	s_movk_i32 s4, 0x75
	s_cselect_b32 s4, s4, 0x74
	s_mul_i32 s4, s4, s1
	s_mul_i32 s1, s1, 33
	s_cselect_b32 s6, s1, s3
	s_add_i32 s4, s4, s5
	s_ashr_i32 s1, s4, 31
	s_lshr_b32 s1, s1, 24
	s_add_i32 s7, s4, s1
	s_ashr_i32 s1, s7, 8
	s_lshl_b32 s1, s1, 3
	s_sub_i32 s3, 29, s1
	s_and_b32 s7, s7, 0xffffff00
	s_min_u32 s3, s3, 8
	s_sub_i32 s4, s4, s7
	s_add_u32 s78, s56, 0x200
	s_addc_u32 s79, s57, 0
	s_add_u32 s66, s56, 0x1000
	s_addc_u32 s67, s57, 0
	s_add_u32 s68, s56, 0x1100
	s_addc_u32 s69, s57, 0
	s_add_u32 s70, s56, 0x1200
	s_addc_u32 s71, s57, 0
	s_add_u32 s72, s56, 0x1300
	s_addc_u32 s73, s57, 0
	s_cmp_eq_u32 s0, 15
	s_cselect_b64 s[8:9], -1, 0
	v_writelane_b32 v253, s8, 5
	s_cmp_eq_u32 s0, 14
	v_cvt_f32_ubyte0_e32 v2, s3
	v_writelane_b32 v253, s9, 6
	s_cselect_b64 s[8:9], -1, 0
	v_writelane_b32 v253, s8, 7
	s_cmp_eq_u32 s0, 13
	v_cvt_f32_i32_e32 v1, s4
	v_writelane_b32 v253, s9, 8
	s_cselect_b64 s[8:9], -1, 0
	v_writelane_b32 v253, s8, 9
	s_cmp_eq_u32 s0, 12
	v_rcp_iflag_f32_e32 v3, v2
	v_writelane_b32 v253, s9, 10
	s_cselect_b64 s[8:9], -1, 0
	v_writelane_b32 v253, s8, 11
	s_cmp_eq_u32 s0, 11
	v_mul_f32_e32 v3, v1, v3
	v_writelane_b32 v253, s9, 12
	s_cselect_b64 s[8:9], -1, 0
	v_writelane_b32 v253, s8, 13
	s_cmp_eq_u32 s0, 10
	v_trunc_f32_e32 v3, v3
	v_writelane_b32 v253, s9, 14
	s_cselect_b64 s[8:9], -1, 0
	v_writelane_b32 v253, s8, 15
	s_cmp_eq_u32 s0, 9
	v_fma_f32 v1, -v3, v2, v1
	v_writelane_b32 v253, s9, 16
	s_cselect_b64 s[8:9], -1, 0
	v_writelane_b32 v253, s8, 17
	s_cmp_eq_u32 s0, 8
	v_cmp_ge_f32_e64 s[14:15], |v1|, v2
	v_writelane_b32 v253, s9, 18
	s_cselect_b64 s[8:9], -1, 0
	v_writelane_b32 v253, s8, 19
	s_cmp_eq_u32 s0, 7
	v_cvt_i32_f32_e32 v1, v3
	v_writelane_b32 v253, s9, 20
	s_cselect_b64 s[8:9], -1, 0
	v_writelane_b32 v253, s8, 21
	s_cmp_eq_u32 s0, 6
	s_mov_b32 s53, 0
	v_writelane_b32 v253, s9, 22
	s_cselect_b64 s[8:9], -1, 0
	v_writelane_b32 v253, s8, 23
	s_cmp_eq_u32 s0, 5
	v_mov_b32_e32 v180, 0x358637bd
	v_writelane_b32 v253, s9, 24
	s_cselect_b64 s[8:9], -1, 0
	v_writelane_b32 v253, s8, 25
	s_cmp_eq_u32 s0, 4
	v_mov_b32_e32 v198, 1
	v_writelane_b32 v253, s9, 26
	s_cselect_b64 s[8:9], -1, 0
	v_writelane_b32 v253, s8, 27
	s_cmp_eq_u32 s0, 3
	v_mov_b32_e32 v199, 0xff800000
	v_writelane_b32 v253, s9, 28
	s_cselect_b64 s[8:9], -1, 0
	v_writelane_b32 v253, s8, 29
	s_cmp_eq_u32 s0, 2
	v_mov_b32_e32 v200, 0x42800000
	v_writelane_b32 v253, s9, 30
	s_cselect_b64 s[8:9], -1, 0
	v_writelane_b32 v253, s8, 31
	s_cmp_eq_u32 s0, 1
	v_mov_b32_e32 v201, 0x42000000
	v_writelane_b32 v253, s9, 32
	s_cselect_b64 s[8:9], -1, 0
	v_writelane_b32 v253, s8, 33
	s_cmp_eq_u32 s0, 0
	v_not_b32_e32 v202, 63
	v_writelane_b32 v253, s9, 34
	s_cselect_b64 s[8:9], -1, 0
	s_lshl_b32 s0, s0, 8
	s_add_u32 s0, s56, s0
	v_writelane_b32 v253, s8, 35
	s_addc_u32 s7, s57, 0
	v_mov_b32_e32 v203, 0x3e38aa3b
	v_writelane_b32 v253, s9, 36
	s_add_u32 s8, s0, 0x1400
	s_addc_u32 s9, s7, 0
	s_add_u32 s54, s0, 0x2400
	v_writelane_b32 v253, s8, 37
	s_addc_u32 s55, s7, 0
	v_mov_b32_e32 v204, 0x7f800000
	v_writelane_b32 v253, s9, 38
	s_add_u32 s8, s56, 0x3400
	s_addc_u32 s9, s57, 0
	v_writelane_b32 v253, s8, 39
	v_mbcnt_hi_u32_b32 v205, -1, v54
	v_mov_b32_e32 v206, 0xc00
	v_writelane_b32 v253, s9, 40
	s_add_u32 s8, s56, 0x3500
	s_addc_u32 s9, s57, 0
	v_writelane_b32 v253, s8, 41
	s_and_b32 s0, s2, 7
	s_lshr_b32 s7, s2, 3
	v_writelane_b32 v253, s9, 42
	s_or_b32 s20, s2, 0x400
	s_add_i32 s10, s7, 29
	s_add_i32 s7, s0, 12
	s_or_b32 s8, s2, 24
	s_cmp_lt_u32 s0, 4
	s_cselect_b32 s11, s7, s8
	s_and_b32 s7, s11, -4
	s_lshl_b32 s52, s10, 8
	s_cmp_eq_u32 s7, 24
	s_cselect_b64 s[8:9], -1, 0
	v_cndmask_b32_e64 v0, 0, 1, s[8:9]
	v_writelane_b32 v253, s8, 43
	s_movk_i32 s80, 0x1080
	s_mov_b64 s[88:89], 0x80000
	v_writelane_b32 v253, s9, 44
	s_and_b64 s[8:9], s[8:9], exec
	s_cselect_b32 s7, s11, s10
	v_writelane_b32 v253, s10, 45
	v_writelane_b32 v253, s11, 46
	s_cselect_b32 s8, s10, s11
	s_lshl_b32 s7, s7, 20
	v_writelane_b32 v253, s7, 47
	s_lshl_b32 s7, s8, 20
	s_cmpk_lt_i32 s20, 0x420
	v_writelane_b32 v253, s7, 48
	s_cselect_b64 s[8:9], -1, 0
	v_writelane_b32 v253, s8, 49
	s_cmpk_lt_i32 s2, 0x140
	s_mov_b64 s[90:91], 0x80
	v_writelane_b32 v253, s9, 50
	s_cselect_b64 s[8:9], -1, 0
	v_writelane_b32 v253, s8, 51
	s_cmpk_lt_i32 s2, 0x100
	s_mov_b64 s[92:93], 0x80080
	v_writelane_b32 v253, s9, 52
	s_cselect_b64 s[8:9], -1, 0
	v_writelane_b32 v253, s8, 53
	s_add_i32 s7, s2, 0xffffff00
	s_lshr_b32 s7, s7, 3
	v_writelane_b32 v253, s9, 54
	v_writelane_b32 v253, s7, 55
	s_add_i32 s7, s0, 1
	s_lshl_b32 s0, s0, 8
	v_writelane_b32 v253, s7, 56
	s_cmpk_lt_u32 s50, 0x41
	v_writelane_b32 v253, s0, 57
	s_cselect_b64 s[8:9], -1, 0
	s_add_i32 s10, s2, 0x700
	v_writelane_b32 v253, s8, 58
	s_cmpk_lt_i32 s2, 0x300
	s_mov_b64 s[96:97], 0x100
	v_writelane_b32 v253, s9, 59
	s_cselect_b64 s[8:9], -1, 0
	v_writelane_b32 v253, s8, 60
	s_cmpk_gt_i32 s2, 0xfdff
	s_cselect_b32 s0, 0x400000, 0
	v_writelane_b32 v253, s9, 61
	s_cselect_b32 s9, 0xfffffb00, 0
	s_cselect_b32 s7, 0x1000000, 0
	s_cselect_b32 s8, 0x800, 0
	s_add_i32 s9, s9, s10
	s_cmpk_gt_i32 s9, 0x3ff
	v_writelane_b32 v253, s10, 62
	s_cselect_b64 s[10:11], -1, 0
	v_writelane_b32 v253, s10, 63
	s_mov_b32 s26, s53
	s_nop 0
	v_writelane_b32 v254, s11, 0
	s_add_i32 s10, s9, 0xfffffc00
	s_lshr_b32 s10, s10, 3
	v_writelane_b32 v254, s10, 1
	s_ashr_i32 s9, s9, 5
	v_writelane_b32 v254, s9, 2
	s_and_b32 s9, s2, 31
	s_cmp_gt_u32 s2, 63
	s_cselect_b64 s[10:11], -1, 0
	v_writelane_b32 v254, s10, 3
	s_add_i32 s12, s2, 0x6c0
	s_nop 0
	v_writelane_b32 v254, s11, 4
	s_sub_i32 s10, s50, 64
	s_cmpk_lt_i32 s12, 0xa00
	v_writelane_b32 v254, s10, 5
	s_cselect_b64 s[10:11], -1, 0
	v_writelane_b32 v254, s10, 6
	s_cmpk_gt_i32 s12, 0x4ff
	s_cselect_b32 s16, 0x400000, 0
	v_writelane_b32 v254, s11, 7
	s_cselect_b32 s11, 0xfffffb00, 0
	s_cselect_b32 s17, 0x1000000, 0
	s_cselect_b32 s10, 0x800, 0
	s_add_i32 s11, s11, s12
	s_cmpk_gt_i32 s11, 0x3ff
	v_writelane_b32 v254, s12, 8
	s_cselect_b64 s[12:13], -1, 0
	s_add_i32 s5, s6, s5
	s_ashr_i32 s6, s5, 31
	s_lshr_b32 s6, s6, 26
	v_writelane_b32 v254, s12, 9
	s_add_i32 s6, s5, s6
	s_nop 0
	v_writelane_b32 v254, s13, 10
	s_and_b32 s12, s6, 0xffc0
	s_sub_i32 s5, s5, s12
	s_bfe_i32 s12, s5, 0x80000
	s_bfe_u32 s12, s12, 0x3000c
	s_add_i32 s12, s5, s12
	s_and_b32 s13, s12, 0xf8
	s_sub_i32 s5, s5, s13
	s_ashr_i32 s6, s6, 6
	s_lshl_b32 s6, s6, 3
	s_sext_i32_i8 s5, s5
	s_add_i32 s5, s6, s5
	v_writelane_b32 v254, s5, 11
	s_add_i32 s5, s11, 0xfffffc00
	s_lshr_b32 s5, s5, 3
	v_writelane_b32 v254, s5, 12
	s_ashr_i32 s5, s11, 5
	v_writelane_b32 v254, s5, 13
	s_bfe_i32 s5, s12, 0x80000
	s_sext_i32_i16 s5, s5
	s_ashr_i32 s5, s5, 3
	v_writelane_b32 v254, s5, 14
	s_lshl_b32 s5, s9, 8
	v_writelane_b32 v254, s5, 15
	s_add_i32 s5, s2, s50
	s_add_i32 s6, s5, 0x400
	s_max_i32 s6, s6, 0x420
	v_readlane_b32 s9, v253, 0
	s_addk_i32 s6, 0xfc00
	s_addk_i32 s9, 0x2000
	v_writelane_b32 v254, s9, 16
	s_cmp_lg_u32 s6, s5
	v_readfirstlane_b32 s9, v1
	v_cvt_f32_u32_e32 v1, s50
	s_cselect_b64 s[12:13], -1, 0
	s_cmp_lg_u64 s[12:13], 0
	s_addc_u32 s5, s2, s50
	s_sub_i32 s5, s6, s5
	s_ashr_i32 s6, s4, 30
	v_rcp_iflag_f32_e32 v1, v1
	s_or_b32 s6, s6, 1
	s_and_b64 s[14:15], s[14:15], exec
	s_cselect_b32 s6, s6, 0
	s_add_i32 s6, s9, s6
	v_mul_f32_e32 v1, 0x4f7ffffe, v1
	s_mul_i32 s3, s6, s3
	v_cvt_u32_f32_e32 v1, v1
	s_sub_i32 s3, s4, s3
	s_sext_i32_i16 s3, s3
	s_add_i32 s1, s1, s3
	v_writelane_b32 v254, s1, 17
	s_sub_i32 s1, 0, s50
	v_readfirstlane_b32 s3, v1
	s_mul_i32 s1, s1, s3
	s_mul_hi_u32 s1, s3, s1
	s_add_i32 s3, s3, s1
	s_mul_hi_u32 s1, s5, s3
	s_mul_i32 s3, s1, s50
	s_sub_i32 s3, s5, s3
	s_add_i32 s4, s1, 1
	s_sub_i32 s5, s3, s50
	s_cmp_ge_u32 s3, s50
	s_cselect_b32 s1, s4, s1
	s_cselect_b32 s3, s5, s3
	s_add_i32 s4, s1, 1
	s_cmp_ge_u32 s3, s50
	s_cselect_b32 s1, s4, s1
	s_cmp_lg_u64 s[12:13], 0
	s_load_dword s3, s[94:95], 0xd8
	s_addc_u32 s1, s1, 1
	v_writelane_b32 v254, s18, 18
	s_cmp_gt_u32 s1, 3
	s_cselect_b64 s[4:5], -1, 0
	v_writelane_b32 v254, s19, 19
	v_writelane_b32 v254, s4, 20
	s_waitcnt lgkmcnt(0)
	s_mul_i32 s51, s51, s3
	v_cndmask_b32_e64 v252, 0, 1, s[18:19]
	v_writelane_b32 v254, s5, 21
	s_and_b32 s4, s1, -4
	s_mul_i32 s3, s4, s50
	v_writelane_b32 v254, s20, 22
	s_add_i32 s3, s20, s3
	v_writelane_b32 v254, s3, 23
	v_writelane_b32 v254, s4, 24
	s_cmp_lg_u32 s1, s4
	s_sext_i32_i16 s1, s6
	v_writelane_b32 v254, s1, 25
	s_cselect_b64 s[4:5], -1, 0
	s_mul_i32 s1, s2, 0x108
	v_writelane_b32 v254, s4, 26
	s_addk_i32 s1, 0xdf00
	s_lshl_b32 s0, s0, 2
	v_writelane_b32 v254, s5, 27
	v_writelane_b32 v254, s1, 28
	v_writelane_b32 v254, s0, 29
	s_lshl_b32 s0, s7, 2
	v_writelane_b32 v254, s0, 30
	s_lshl_b32 s0, s16, 2
	v_writelane_b32 v254, s0, 31
	s_lshl_b32 s0, s17, 2
	v_writelane_b32 v254, s0, 32
	v_sub_co_u32_e64 v2, s[0:1], s2, 32
	s_lshl_b32 s4, s8, 2
	s_nop 0
	v_writelane_b32 v254, s0, 33
	s_ashr_i32 s39, s38, 31
	s_lshl_b64 s[12:13], s[52:53], 2
	v_writelane_b32 v254, s1, 34
	v_readfirstlane_b32 s0, v2
	s_brev_b32 s20, 63
	v_mov_b32_e32 v1, 0
	v_writelane_b32 v254, s0, 35
	v_readfirstlane_b32 s0, v0
	s_mov_b32 s7, 0x800000
	s_mov_b32 s9, 0xc2fc0000
	v_writelane_b32 v254, s0, 36
	s_max_u32 s0, s50, 1
	v_writelane_b32 v254, s0, 37
	s_add_i32 s0, 0, 0x24010
	v_writelane_b32 v254, s0, 38
	s_add_i32 s0, 0, 0x24014
	v_writelane_b32 v254, s0, 39
	v_writelane_b32 v254, s4, 40
	s_mov_b32 s14, 0x42000
	s_mov_b32 s15, 0x80000
	v_writelane_b32 v254, s5, 41
	s_lshl_b32 s4, s10, 2
	v_writelane_b32 v254, s4, 42
	s_add_i32 s0, 0, 0x24000
	s_mov_b32 s6, 0x358637bd
	v_writelane_b32 v254, s5, 43
	v_cmp_gt_u32_e64 s[4:5], 32, v2
	s_mov_b32 s8, 0x45800000
	s_mov_b32 s10, 0x3db504f3
	v_writelane_b32 v254, s4, 44
	s_mov_b64 s[16:17], 0x100000
	s_mov_b32 s21, -1
	v_writelane_b32 v254, s5, 45
	s_lshl_b64 s[4:5], s[38:39], 13
	v_writelane_b32 v254, s4, 46
	s_barrier
	s_nop 0
	v_writelane_b32 v254, s5, 47
	s_lshl_b64 s[4:5], s[38:39], 2
	v_writelane_b32 v254, s4, 48
	s_nop 1
	v_writelane_b32 v254, s5, 49
	s_lshl_b64 s[4:5], s[38:39], 12
	v_writelane_b32 v254, s4, 50
	s_nop 1
	v_writelane_b32 v254, s5, 51
	s_mov_b64 s[4:5], -1
	v_writelane_b32 v254, s4, 52
	s_nop 1
	v_writelane_b32 v254, s5, 53
	v_writelane_b32 v254, s12, 54
	s_mov_b32 s4, 0x3a000000
	s_nop 0
	v_writelane_b32 v254, s13, 55
	v_writelane_b32 v254, s78, 56
	s_mov_b64 s[12:13], 0x1800
	s_nop 0
	v_writelane_b32 v254, s79, 57
	v_writelane_b32 v254, s94, 58
	s_nop 1
	v_writelane_b32 v254, s95, 59
	v_writelane_b32 v254, s38, 60
	s_nop 1
	v_writelane_b32 v254, s39, 61
	v_writelane_b32 v254, s54, 62
	s_nop 1
	v_writelane_b32 v254, s55, 63
	s_branch .LBB0_105
